# adds: GEMM phase prologue de-serialised - all 14 first-tile LDS-DMA loads issued before the first wait (vmcnt(2)->vmcnt(8) moved below the second load group)
# speedup vs baseline: 1.0011x; 1.0011x over previous
; #define PG8_STAGE(bufoff, gbase, voff) do { _Pragma("unroll") for (int _i = 0; _i < 2; ++_i) \
;         __builtin_amdgcn_global_load_lds((const unsigned*)((const char*)(gbase) + (voff)[_i]), (LAS unsigned*)(lds + (bufoff) + ldsw + _i * 8192), 16, 0, 0); } while (0)
; #define PG8_WAIT_V(n) asm volatile("s_waitcnt vmcnt(" #n ")" ::: "memory")
; #define PG8_BAR __builtin_amdgcn_s_barrier()
; template <class Epi>
; __device__ __forceinline__ void gemm_phase(LAS unsigned char* lds, const Gemm g, const TileOrder& S, const Epi& E) {
;     ...
;     for (int i = 0; i < 2; ++i) { int R, C; stage_rc(tid * 16 + i * 8192, R, C); const int Rb = Epi::PERM ? ((R & ~31) + perm32(R & 31)) : R;
;         voffA[i] = (unsigned)(R * (g.a_tiled ? 64 : g.lda) + C) * 2u; voffB[i] = (unsigned)(Rb * g.ldb + C) * 2u; }
;     const size_t kstep = (size_t)(BK * 2);
;     const size_t kstepA = g.a_tiled ? (size_t)32768 : kstep;
;     const size_t hstepA = g.a_tiled ? (size_t)16384 : (size_t)HALF * g.lda * 2, tstepA = g.a_tiled ? (size_t)(g.K / 64) * 32768 : 2 * hstepA;
;     const size_t hstepB = (size_t)HALF * g.ldb * 2, tstepB = 2 * hstepB;
;     const unsigned ldsw = (unsigned)wid * 1024u;
;     const int aoff = lds_byte(wr * 64 + fr, fq * 8), boff = lds_byte(wc * 32 + fr, fq * 8);
;     ...
;     PG8_STAGE(PG8_SB(0, 0), cB, voffB); PG8_STAGE(PG8_SB(0, 1), cB + hstepB, voffB); PG8_STAGE(PG8_SA(0, 0), cA, voffA); PG8_STAGE(PG8_SA(0, 1), cA + hstepA, voffA);
;     if (wr == 1) PG8_BAR;
;     PG8_WAIT_V(2); PG8_BAR;
;     PG8_STAGE(PG8_SB(1, 0), cB + kstep, voffB); PG8_STAGE(PG8_SA(1, 0), cA + kstepA, voffA); PG8_STAGE(PG8_SB(1, 1), cB + hstepB + kstep, voffB);
;     PG8_WAIT_V(6); PG8_BAR;
.LBB0_45:
	s_lshl_b32 s26, s84, 21
	s_lshl_b64 s[16:17], s[26:27], 2
	v_readlane_b32 s12, v252, 52
	s_add_u32 s12, s12, s16
	v_readlane_b32 s13, v252, 53
	s_addc_u32 s13, s13, s17
	v_readlane_b32 s28, v254, 3
	s_add_u32 s42, s12, 0x2000000
	v_readlane_b32 s29, v254, 4
	s_addc_u32 s43, s13, 0
	s_and_b32 s26, s15, 3
	s_add_i32 m0, s56, 0x18000
	v_lshl_add_u64 v[2:3], v[2:3], 0, s[34:35]
	v_lshl_add_u64 v[12:13], s[28:29], 0, v[148:149]
	s_lshl_b32 s60, s14, 6
	s_lshl_b32 s12, s14, 13
	s_lshl_b32 s13, s26, 12
	global_load_lds_dwordx4 v[2:3], off
	v_lshl_add_u64 v[2:3], v[4:5], 0, s[34:35]
	s_add_i32 m0, s56, 0x1a000
	s_add_i32 s61, s56, 0x8000
	s_add_i32 s62, s56, 0xa000
	v_lshl_add_u64 v[14:15], s[28:29], 0, v[146:147]
	global_load_lds_dwordx4 v[2:3], off
	v_lshl_add_u64 v[2:3], v[12:13], 0, s[34:35]
	s_mov_b32 m0, s61
	s_add_u32 s16, s2, 0x80080
	global_load_lds_dwordx4 v[2:3], off
	v_lshl_add_u64 v[2:3], v[14:15], 0, s[34:35]
	s_mov_b32 m0, s62
	s_addc_u32 s17, s3, 0
	global_load_lds_dwordx4 v[2:3], off
	s_add_i32 m0, s56, 0x1c000
	v_lshl_add_u64 v[2:3], s[16:17], 0, v[148:149]
	global_load_lds_dwordx4 v[2:3], off
	v_lshl_add_u64 v[2:3], s[16:17], 0, v[146:147]
	s_add_i32 m0, s56, 0x1e000
	v_bfe_u32 v185, v6, 4, 2
	global_load_lds_dwordx4 v[2:3], off
	s_waitcnt vmcnt(8)
	s_barrier
	v_and_b32_e32 v184, 15, v6
	v_lshlrev_b32_e32 v2, 4, v185
	v_lshlrev_b32_e32 v3, 2, v6
	v_lshl_or_b32 v2, v184, 6, v2
	v_and_b32_e32 v3, 32, v3
	v_bitop3_b32 v4, v2, s12, v3 bitop3:0xde
	v_bitop3_b32 v186, v2, s13, v3 bitop3:0xde
	v_lshlrev_b32_e32 v2, 15, v9
	v_and_b32_e32 v2, 0xffff0000, v2
	v_lshl_add_u32 v2, v10, 12, v2
	v_and_b32_e32 v3, 1, v9
	v_lshl_or_b32 v2, v3, 6, v2
	v_lshl_add_u32 v150, v11, 1, v2
	v_lshlrev_b32_e32 v2, 15, v0
	s_cmpk_lt_u32 s6, 0x100
	v_and_b32_e32 v2, 0xffff0000, v2
	s_waitcnt vmcnt(6)
	s_cselect_b64 s[44:45], -1, 0
	s_lshl_b32 s6, s14, 8
	v_lshl_add_u32 v2, v7, 12, v2
	v_and_b32_e32 v0, 1, v0
	s_add_i32 s63, s6, 0
	v_lshl_or_b32 v0, v0, 6, v2
	s_add_i32 s63, s63, 0x20000
	s_lshl_b32 s64, s26, 6
	v_mov_b32_e32 v151, v1
	v_lshl_add_u32 v152, v8, 1, v0
	v_mov_b32_e32 v153, v1
	s_mov_b32 s65, 0
	s_mov_b32 s41, -1
	v_add_u32_e32 v187, 0, v4
	v_readlane_b32 s67, v253, 62
	v_readlane_b32 s48, v254, 1
	s_barrier
	v_readlane_b32 s49, v254, 2
	s_branch .LBB0_48

; #define PG8_STAGE(bufoff, gbase, voff) do { _Pragma("unroll") for (int _i = 0; _i < 2; ++_i) \
;         __builtin_amdgcn_global_load_lds((const unsigned*)((const char*)(gbase) + (voff)[_i]), (LAS unsigned*)(lds + (bufoff) + ldsw + _i * 8192), 16, 0, 0); } while (0)
; #define PG8_WAIT_V(n) asm volatile("s_waitcnt vmcnt(" #n ")" ::: "memory")
; #define PG8_BAR __builtin_amdgcn_s_barrier()
; template <class Epi>
; __device__ __forceinline__ void gemm_phase(LAS unsigned char* lds, const Gemm g, const TileOrder& S, const Epi& E) {
;     ...
;     for (int i = 0; i < 2; ++i) { int R, C; stage_rc(tid * 16 + i * 8192, R, C); const int Rb = Epi::PERM ? ((R & ~31) + perm32(R & 31)) : R;
;         voffA[i] = (unsigned)(R * (g.a_tiled ? 64 : g.lda) + C) * 2u; voffB[i] = (unsigned)(Rb * g.ldb + C) * 2u; }
;     const size_t kstep = (size_t)(BK * 2);
;     const size_t kstepA = g.a_tiled ? (size_t)32768 : kstep;
;     const size_t hstepA = g.a_tiled ? (size_t)16384 : (size_t)HALF * g.lda * 2, tstepA = g.a_tiled ? (size_t)(g.K / 64) * 32768 : 2 * hstepA;
;     const size_t hstepB = (size_t)HALF * g.ldb * 2, tstepB = 2 * hstepB;
;     const unsigned ldsw = (unsigned)wid * 1024u;
;     const int aoff = lds_byte(wr * 64 + fr, fq * 8), boff = lds_byte(wc * 32 + fr, fq * 8);
;     ...
;     PG8_STAGE(PG8_SB(0, 0), cB, voffB); PG8_STAGE(PG8_SB(0, 1), cB + hstepB, voffB); PG8_STAGE(PG8_SA(0, 0), cA, voffA); PG8_STAGE(PG8_SA(0, 1), cA + hstepA, voffA);
;     if (wr == 1) PG8_BAR;
;     PG8_WAIT_V(2); PG8_BAR;
;     PG8_STAGE(PG8_SB(1, 0), cB + kstep, voffB); PG8_STAGE(PG8_SA(1, 0), cA + kstepA, voffA); PG8_STAGE(PG8_SB(1, 1), cB + hstepB + kstep, voffB);
;     PG8_WAIT_V(6); PG8_BAR;
.LBB0_245:
	s_lshl_b32 s26, s24, 21
	s_lshl_b64 s[12:13], s[26:27], 2
	v_readlane_b32 s14, v252, 52
	s_add_u32 s26, s14, s12
	v_readlane_b32 s12, v252, 53
	s_addc_u32 s56, s12, s13
	s_add_i32 m0, s52, 0x18000
	v_lshl_add_u64 v[2:3], v[2:3], 0, s[34:35]
	v_readlane_b32 s12, v254, 53
	v_mov_b32_e32 v195, v1
	s_and_b32 s57, s6, 3
	global_load_lds_dwordx4 v[2:3], off
	v_lshl_add_u64 v[2:3], v[4:5], 0, s[34:35]
	s_add_i32 m0, s52, 0x1a000
	v_readlane_b32 s13, v254, 54
	s_add_i32 s60, s52, 0x8000
	v_mov_b32_e32 v193, v1
	s_lshl_b32 s58, s1, 6
	s_lshl_b32 s1, s1, 13
	s_lshl_b32 s59, s57, 5
	s_lshl_b32 s6, s57, 12
	global_load_lds_dwordx4 v[2:3], off
	v_lshl_add_u64 v[2:3], s[12:13], 0, v[194:195]
	s_mov_b32 m0, s60
	s_add_i32 s61, s52, 0xa000
	global_load_lds_dwordx4 v[2:3], off
	v_lshl_add_u64 v[2:3], s[12:13], 0, v[192:193]
	s_add_u32 s12, s2, 0x80080
	s_mov_b32 m0, s61
	s_addc_u32 s13, s3, 0
	global_load_lds_dwordx4 v[2:3], off
	s_add_i32 m0, s52, 0x1c000
	v_lshl_add_u64 v[2:3], s[12:13], 0, v[0:1]
	global_load_lds_dwordx4 v[2:3], off
	v_lshl_add_u64 v[2:3], s[12:13], 0, v[190:191]
	s_add_i32 m0, s52, 0x1e000
	v_bfe_u32 v228, v6, 4, 2
	global_load_lds_dwordx4 v[2:3], off
	s_waitcnt vmcnt(8)
	s_barrier
	v_and_b32_e32 v229, 15, v6
	v_lshlrev_b32_e32 v2, 4, v228
	v_lshlrev_b32_e32 v3, 2, v6
	v_lshl_or_b32 v2, v229, 6, v2
	v_and_b32_e32 v3, 32, v3
	v_bitop3_b32 v4, v2, s1, v3 bitop3:0xde
	v_bitop3_b32 v238, v2, s6, v3 bitop3:0xde
	v_lshlrev_b32_e32 v2, 10, v11
	v_and_b32_e32 v2, 0xfffff800, v2
	v_lshl_add_u32 v2, v10, 7, v2
	v_and_b32_e32 v3, 1, v11
	v_lshl_or_b32 v2, v3, 6, v2
	v_lshl_add_u32 v196, v12, 1, v2
	v_lshlrev_b32_e32 v2, 10, v7
	v_and_b32_e32 v2, 0xfffff800, v2
	s_waitcnt vmcnt(6)
	v_lshl_add_u32 v2, v8, 7, v2
	v_and_b32_e32 v3, 1, v7
	s_cmpk_lt_u32 s0, 0x100
	v_lshl_or_b32 v2, v3, 6, v2
	v_readlane_b32 s0, v255, 3
	v_readlane_b32 s28, v254, 51
	s_cselect_b64 s[36:37], -1, 0
	v_mov_b32_e32 v197, v1
	v_lshl_add_u32 v198, v9, 1, v2
	v_mov_b32_e32 v199, v1
	s_mov_b32 s62, 0
	v_add_u32_e32 v239, 0, v4
	v_readlane_b32 s63, v254, 7
	s_mov_b32 s41, s0
	v_readlane_b32 s29, v254, 52
	s_barrier
	v_readlane_b32 s1, v255, 4
	s_branch .LBB0_248

; #define PG8_STAGE(bufoff, gbase, voff) do { _Pragma("unroll") for (int _i = 0; _i < 2; ++_i) \
;         __builtin_amdgcn_global_load_lds((const unsigned*)((const char*)(gbase) + (voff)[_i]), (LAS unsigned*)(lds + (bufoff) + ldsw + _i * 8192), 16, 0, 0); } while (0)
; #define PG8_WAIT_V(n) asm volatile("s_waitcnt vmcnt(" #n ")" ::: "memory")
; #define PG8_BAR __builtin_amdgcn_s_barrier()
; template <class Epi>
; __device__ __forceinline__ void gemm_phase(LAS unsigned char* lds, const Gemm g, const TileOrder& S, const Epi& E) {
;     ...
;     for (int i = 0; i < 2; ++i) { int R, C; stage_rc(tid * 16 + i * 8192, R, C); const int Rb = Epi::PERM ? ((R & ~31) + perm32(R & 31)) : R;
;         voffA[i] = (unsigned)(R * (g.a_tiled ? 64 : g.lda) + C) * 2u; voffB[i] = (unsigned)(Rb * g.ldb + C) * 2u; }
;     const size_t kstep = (size_t)(BK * 2);
;     const size_t kstepA = g.a_tiled ? (size_t)32768 : kstep;
;     const size_t hstepA = g.a_tiled ? (size_t)16384 : (size_t)HALF * g.lda * 2, tstepA = g.a_tiled ? (size_t)(g.K / 64) * 32768 : 2 * hstepA;
;     const size_t hstepB = (size_t)HALF * g.ldb * 2, tstepB = 2 * hstepB;
;     const unsigned ldsw = (unsigned)wid * 1024u;
;     const int aoff = lds_byte(wr * 64 + fr, fq * 8), boff = lds_byte(wc * 32 + fr, fq * 8);
;     ...
;     PG8_STAGE(PG8_SB(0, 0), cB, voffB); PG8_STAGE(PG8_SB(0, 1), cB + hstepB, voffB); PG8_STAGE(PG8_SA(0, 0), cA, voffA); PG8_STAGE(PG8_SA(0, 1), cA + hstepA, voffA);
;     if (wr == 1) PG8_BAR;
;     PG8_WAIT_V(2); PG8_BAR;
;     PG8_STAGE(PG8_SB(1, 0), cB + kstep, voffB); PG8_STAGE(PG8_SA(1, 0), cA + kstepA, voffA); PG8_STAGE(PG8_SB(1, 1), cB + hstepB + kstep, voffB);
;     PG8_WAIT_V(6); PG8_BAR;
.LBB0_445:
	v_readlane_b32 s4, v254, 17
	v_readlane_b32 s5, v254, 18
	v_mov_b32_e32 v131, v1
	v_readlane_b32 s44, v254, 13
	v_lshl_add_u64 v[12:13], s[4:5], 0, v[0:1]
	v_lshl_add_u64 v[14:15], s[4:5], 0, v[130:131]
	v_mov_b32_e32 v135, v1
	v_readlane_b32 s45, v254, 14
	s_add_i32 m0, s26, 0x18000
	v_lshl_add_u64 v[12:13], v[12:13], 0, s[34:35]
	v_lshl_add_u64 v[16:17], s[44:45], 0, v[134:135]
	v_mov_b32_e32 v133, v1
	global_load_lds_dwordx4 v[12:13], off
	v_lshl_add_u64 v[12:13], v[14:15], 0, s[34:35]
	s_add_i32 m0, s26, 0x1a000
	s_add_i32 s51, s26, 0x8000
	v_lshl_add_u64 v[18:19], s[44:45], 0, v[132:133]
	global_load_lds_dwordx4 v[12:13], off
	v_lshl_add_u64 v[12:13], v[16:17], 0, s[34:35]
	s_mov_b32 m0, s51
	s_add_i32 s52, s26, 0xa000
	v_readlane_b32 s12, v254, 19
	global_load_lds_dwordx4 v[12:13], off
	v_lshl_add_u64 v[12:13], v[18:19], 0, s[34:35]
	s_mov_b32 m0, s52
	v_readlane_b32 s13, v254, 20
	global_load_lds_dwordx4 v[12:13], off
	s_add_i32 m0, s26, 0x1c000
	v_lshl_add_u64 v[12:13], s[12:13], 0, v[0:1]
	global_load_lds_dwordx4 v[12:13], off
	v_lshl_add_u64 v[12:13], s[12:13], 0, v[130:131]
	s_add_i32 m0, s26, 0x1e000
	v_bfe_u32 v141, v4, 4, 2
	global_load_lds_dwordx4 v[12:13], off
	s_waitcnt vmcnt(8)
	s_barrier
	v_and_b32_e32 v140, 15, v4
	v_lshlrev_b32_e32 v11, 4, v141
	v_lshlrev_b32_e32 v4, 2, v4
	s_lshl_b32 s1, s1, 5
	s_lshl_b32 s53, s2, 6
	v_lshl_or_b32 v11, v140, 6, v11
	s_lshl_b32 s2, s2, 13
	v_and_b32_e32 v4, 32, v4
	s_and_b32 s54, s1, 0x60
	v_bitop3_b32 v12, v11, s2, v4 bitop3:0xde
	s_lshl_b32 s1, s54, 7
	s_movk_i32 s2, 0x300
	v_bitop3_b32 v142, v11, s1, v4 bitop3:0xde
	v_lshrrev_b32_e32 v8, 1, v8
	v_mul_lo_u32 v4, v10, s2
	s_movk_i32 s3, 0x3000
	s_cmpk_lt_u32 s0, 0x100
	v_mad_u64_u32 v[10:11], s[0:1], v8, s3, v[4:5]
	v_or_b32_e32 v4, v10, v7
	v_add_lshl_u32 v8, v4, v9, 1
	v_lshrrev_b32_e32 v3, 1, v3
	v_mul_lo_u32 v4, v6, s2
	v_mad_u64_u32 v[6:7], s[0:1], v3, s3, v[4:5]
	s_waitcnt vmcnt(6)
	v_or_b32_e32 v2, v6, v2
	v_mov_b32_e32 v9, v1
	s_mov_b64 s[12:13], 0x30080
	v_add_lshl_u32 v2, v2, v5, 1
	v_mov_b32_e32 v3, v1
	s_cselect_b64 s[36:37], -1, 0
	v_lshl_add_u64 v[136:137], v[8:9], 0, s[12:13]
	v_lshl_add_u64 v[138:139], v[2:3], 0, s[12:13]
	s_mov_b32 s41, 0
	v_add_u32_e32 v143, 0, v12
	v_readlane_b32 s56, v254, 12
	s_mov_b64 s[2:3], s[4:5]
	s_barrier
	s_branch .LBB0_448

; #define PG8_STAGE(bufoff, gbase, voff) do { _Pragma("unroll") for (int _i = 0; _i < 2; ++_i) \
;         __builtin_amdgcn_global_load_lds((const unsigned*)((const char*)(gbase) + (voff)[_i]), (LAS unsigned*)(lds + (bufoff) + ldsw + _i * 8192), 16, 0, 0); } while (0)
; #define PG8_WAIT_V(n) asm volatile("s_waitcnt vmcnt(" #n ")" ::: "memory")
; #define PG8_BAR __builtin_amdgcn_s_barrier()
; template <class Epi>
; __device__ __forceinline__ void gemm_phase(LAS unsigned char* lds, const Gemm g, const TileOrder& S, const Epi& E) {
;     ...
;     for (int i = 0; i < 2; ++i) { int R, C; stage_rc(tid * 16 + i * 8192, R, C); const int Rb = Epi::PERM ? ((R & ~31) + perm32(R & 31)) : R;
;         voffA[i] = (unsigned)(R * (g.a_tiled ? 64 : g.lda) + C) * 2u; voffB[i] = (unsigned)(Rb * g.ldb + C) * 2u; }
;     const size_t kstep = (size_t)(BK * 2);
;     const size_t kstepA = g.a_tiled ? (size_t)32768 : kstep;
;     const size_t hstepA = g.a_tiled ? (size_t)16384 : (size_t)HALF * g.lda * 2, tstepA = g.a_tiled ? (size_t)(g.K / 64) * 32768 : 2 * hstepA;
;     const size_t hstepB = (size_t)HALF * g.ldb * 2, tstepB = 2 * hstepB;
;     const unsigned ldsw = (unsigned)wid * 1024u;
;     const int aoff = lds_byte(wr * 64 + fr, fq * 8), boff = lds_byte(wc * 32 + fr, fq * 8);
;     ...
;     PG8_STAGE(PG8_SB(0, 0), cB, voffB); PG8_STAGE(PG8_SB(0, 1), cB + hstepB, voffB); PG8_STAGE(PG8_SA(0, 0), cA, voffA); PG8_STAGE(PG8_SA(0, 1), cA + hstepA, voffA);
;     if (wr == 1) PG8_BAR;
;     PG8_WAIT_V(2); PG8_BAR;
;     PG8_STAGE(PG8_SB(1, 0), cB + kstep, voffB); PG8_STAGE(PG8_SA(1, 0), cA + kstepA, voffA); PG8_STAGE(PG8_SB(1, 1), cB + hstepB + kstep, voffB);
;     PG8_WAIT_V(6); PG8_BAR;
.LBB0_582:
	v_readlane_b32 s52, v252, 2
	v_readlane_b32 s53, v252, 3
	v_readlane_b32 s12, v254, 31
	v_readlane_b32 s54, v252, 4
	v_readlane_b32 s55, v252, 5
	v_readlane_b32 s56, v252, 6
	v_readlane_b32 s57, v252, 7
	s_mov_b64 s[40:41], s[52:53]
	v_readlane_b32 s13, v254, 32
	s_lshl_b64 s[14:15], s[84:85], 13
	s_mov_b64 s[44:45], s[56:57]
	v_lshl_add_u64 v[12:13], s[12:13], 0, v[0:1]
	v_mov_b32_e32 v209, v1
	v_readlane_b32 s28, v254, 27
	s_add_u32 s36, s44, s14
	v_lshl_add_u64 v[14:15], s[12:13], 0, v[208:209]
	v_mov_b32_e32 v213, v1
	v_readlane_b32 s29, v254, 28
	s_addc_u32 s37, s45, s15
	s_add_i32 m0, s26, 0x18000
	v_lshl_add_u64 v[12:13], v[12:13], 0, s[34:35]
	v_lshl_add_u64 v[16:17], s[28:29], 0, v[212:213]
	v_mov_b32_e32 v211, v1
	global_load_lds_dwordx4 v[12:13], off
	v_lshl_add_u64 v[12:13], v[14:15], 0, s[34:35]
	s_add_i32 m0, s26, 0x1a000
	s_add_i32 s51, s26, 0x8000
	v_lshl_add_u64 v[18:19], s[28:29], 0, v[210:211]
	s_mov_b64 s[42:43], s[54:55]
	global_load_lds_dwordx4 v[12:13], off
	v_lshl_add_u64 v[12:13], v[16:17], 0, s[34:35]
	s_mov_b32 m0, s51
	s_add_i32 s52, s26, 0xa000
	v_readlane_b32 s14, v254, 33
	global_load_lds_dwordx4 v[12:13], off
	v_lshl_add_u64 v[12:13], v[18:19], 0, s[34:35]
	s_mov_b32 m0, s52
	v_readlane_b32 s15, v254, 34
	global_load_lds_dwordx4 v[12:13], off
	s_add_i32 m0, s26, 0x1c000
	v_lshl_add_u64 v[12:13], s[14:15], 0, v[0:1]
	global_load_lds_dwordx4 v[12:13], off
	v_lshl_add_u64 v[12:13], s[14:15], 0, v[208:209]
	s_add_i32 m0, s26, 0x1e000
	v_bfe_u32 v223, v3, 4, 2
	global_load_lds_dwordx4 v[12:13], off
	s_waitcnt vmcnt(8)
	s_barrier
	v_and_b32_e32 v222, 15, v3
	v_lshlrev_b32_e32 v11, 4, v223
	v_lshlrev_b32_e32 v3, 2, v3
	s_lshl_b32 s1, s1, 5
	s_lshl_b32 s53, s2, 6
	v_lshl_or_b32 v11, v222, 6, v11
	s_lshl_b32 s2, s2, 13
	v_and_b32_e32 v3, 32, v3
	s_and_b32 s54, s1, 0x60
	v_bitop3_b32 v14, v11, s2, v3 bitop3:0xde
	s_lshl_b32 s1, s54, 7
	s_movk_i32 s2, 0x300
	v_bitop3_b32 v224, v11, s1, v3 bitop3:0xde
	v_lshrrev_b32_e32 v3, 1, v8
	v_mul_lo_u32 v8, v7, s2
	s_movk_i32 s3, 0x3000
	s_cmpk_lt_u32 s0, 0x100
	v_mad_u64_u32 v[12:13], s[0:1], v3, s3, v[8:9]
	v_or_b32_e32 v3, v12, v9
	v_add_lshl_u32 v8, v3, v10, 1
	v_lshrrev_b32_e32 v3, 1, v2
	v_mul_lo_u32 v2, v4, s2
	v_mad_u64_u32 v[2:3], s[0:1], v3, s3, v[2:3]
	s_waitcnt vmcnt(6)
	v_or_b32_e32 v2, v2, v5
	v_readlane_b32 s59, v252, 9
	v_mov_b32_e32 v9, v1
	s_mov_b64 s[14:15], 0x30080
	v_add_lshl_u32 v2, v2, v6, 1
	v_mov_b32_e32 v3, v1
	v_readlane_b32 s58, v252, 8
	s_cselect_b64 s[42:43], -1, 0
	v_lshl_add_u64 v[214:215], v[8:9], 0, s[14:15]
	v_lshl_add_u64 v[216:217], v[2:3], 0, s[14:15]
	s_mov_b32 s55, 0
	v_add_u32_e32 v225, 0, v14
	v_readlane_b32 s41, v254, 21
	v_readlane_b32 s59, v254, 26
	s_mov_b64 s[2:3], s[12:13]
	v_readlane_b32 s60, v252, 10
	v_readlane_b32 s61, v252, 11
	v_readlane_b32 s62, v252, 12
	v_readlane_b32 s63, v252, 13
	v_readlane_b32 s64, v252, 14
	v_readlane_b32 s65, v252, 15
	v_readlane_b32 s66, v252, 16
	v_readlane_b32 s67, v252, 17
	s_barrier
	s_branch .LBB0_585

; #define PG8_STAGE(bufoff, gbase, voff) do { _Pragma("unroll") for (int _i = 0; _i < 2; ++_i) \
;         __builtin_amdgcn_global_load_lds((const unsigned*)((const char*)(gbase) + (voff)[_i]), (LAS unsigned*)(lds + (bufoff) + ldsw + _i * 8192), 16, 0, 0); } while (0)
; #define PG8_WAIT_V(n) asm volatile("s_waitcnt vmcnt(" #n ")" ::: "memory")
; #define PG8_BAR __builtin_amdgcn_s_barrier()
; template <class Epi>
; __device__ __forceinline__ void gemm_phase(LAS unsigned char* lds, const Gemm g, const TileOrder& S, const Epi& E) {
;     ...
;     for (int i = 0; i < 2; ++i) { int R, C; stage_rc(tid * 16 + i * 8192, R, C); const int Rb = Epi::PERM ? ((R & ~31) + perm32(R & 31)) : R;
;         voffA[i] = (unsigned)(R * (g.a_tiled ? 64 : g.lda) + C) * 2u; voffB[i] = (unsigned)(Rb * g.ldb + C) * 2u; }
;     const size_t kstep = (size_t)(BK * 2);
;     const size_t kstepA = g.a_tiled ? (size_t)32768 : kstep;
;     const size_t hstepA = g.a_tiled ? (size_t)16384 : (size_t)HALF * g.lda * 2, tstepA = g.a_tiled ? (size_t)(g.K / 64) * 32768 : 2 * hstepA;
;     const size_t hstepB = (size_t)HALF * g.ldb * 2, tstepB = 2 * hstepB;
;     const unsigned ldsw = (unsigned)wid * 1024u;
;     const int aoff = lds_byte(wr * 64 + fr, fq * 8), boff = lds_byte(wc * 32 + fr, fq * 8);
;     ...
;     PG8_STAGE(PG8_SB(0, 0), cB, voffB); PG8_STAGE(PG8_SB(0, 1), cB + hstepB, voffB); PG8_STAGE(PG8_SA(0, 0), cA, voffA); PG8_STAGE(PG8_SA(0, 1), cA + hstepA, voffA);
;     if (wr == 1) PG8_BAR;
;     PG8_WAIT_V(2); PG8_BAR;
;     PG8_STAGE(PG8_SB(1, 0), cB + kstep, voffB); PG8_STAGE(PG8_SA(1, 0), cA + kstepA, voffA); PG8_STAGE(PG8_SB(1, 1), cB + hstepB + kstep, voffB);
;     PG8_WAIT_V(6); PG8_BAR;
.LBB0_658:
	s_lshl_b32 s26, s24, 21
	s_lshl_b64 s[14:15], s[26:27], 2
	v_readlane_b32 s5, v252, 52
	v_readlane_b32 s12, v254, 61
	s_add_u32 s26, s5, s14
	v_readlane_b32 s5, v252, 53
	v_mov_b32_e32 v159, v1
	v_readlane_b32 s13, v254, 62
	s_addc_u32 s54, s5, s15
	s_and_b32 s55, s4, 3
	s_add_i32 m0, s50, 0x18000
	v_lshl_add_u64 v[2:3], v[2:3], 0, s[34:35]
	v_lshl_add_u64 v[14:15], s[12:13], 0, v[158:159]
	v_mov_b32_e32 v157, v1
	s_lshl_b32 s56, s1, 6
	s_lshl_b32 s1, s1, 13
	s_lshl_b32 s57, s55, 5
	s_lshl_b32 s6, s55, 12
	global_load_lds_dwordx4 v[2:3], off
	v_lshl_add_u64 v[2:3], v[4:5], 0, s[34:35]
	s_add_i32 m0, s50, 0x1a000
	s_add_i32 s58, s50, 0x8000
	s_add_i32 s59, s50, 0xa000
	v_lshl_add_u64 v[16:17], s[12:13], 0, v[156:157]
	global_load_lds_dwordx4 v[2:3], off
	v_lshl_add_u64 v[2:3], v[14:15], 0, s[34:35]
	s_mov_b32 m0, s58
	s_add_u32 s4, s2, 0x80080
	global_load_lds_dwordx4 v[2:3], off
	v_lshl_add_u64 v[2:3], v[16:17], 0, s[34:35]
	s_mov_b32 m0, s59
	s_addc_u32 s5, s3, 0
	global_load_lds_dwordx4 v[2:3], off
	s_add_i32 m0, s50, 0x1c000
	v_lshl_add_u64 v[2:3], s[4:5], 0, v[0:1]
	global_load_lds_dwordx4 v[2:3], off
	v_lshl_add_u64 v[2:3], s[4:5], 0, v[154:155]
	s_add_i32 m0, s50, 0x1e000
	v_bfe_u32 v183, v6, 4, 2
	global_load_lds_dwordx4 v[2:3], off
	s_waitcnt vmcnt(8)
	s_barrier
	v_and_b32_e32 v182, 15, v6
	v_lshlrev_b32_e32 v2, 4, v183
	v_lshlrev_b32_e32 v3, 2, v6
	v_lshl_or_b32 v2, v182, 6, v2
	v_and_b32_e32 v3, 32, v3
	v_bitop3_b32 v4, v2, s1, v3 bitop3:0xde
	v_bitop3_b32 v184, v2, s6, v3 bitop3:0xde
	v_lshlrev_b32_e32 v2, 15, v11
	v_and_b32_e32 v2, 0xffff0000, v2
	v_lshl_add_u32 v2, v10, 12, v2
	v_and_b32_e32 v3, 1, v11
	v_lshl_or_b32 v2, v3, 6, v2
	v_lshl_add_u32 v160, v12, 1, v2
	v_lshlrev_b32_e32 v2, 15, v7
	v_and_b32_e32 v2, 0xffff0000, v2
	s_waitcnt vmcnt(6)
	v_lshl_add_u32 v2, v8, 12, v2
	v_and_b32_e32 v3, 1, v7
	s_cmpk_lt_u32 s0, 0x100
	v_lshl_or_b32 v2, v3, 6, v2
	v_readlane_b32 s0, v254, 57
	s_cselect_b64 s[38:39], -1, 0
	v_mov_b32_e32 v161, v1
	v_lshl_add_u32 v162, v9, 1, v2
	v_mov_b32_e32 v163, v1
	s_mov_b32 s60, 0
	v_add_u32_e32 v185, 0, v4
	v_readlane_b32 s41, v254, 38
	s_mov_b32 s61, s0
	s_mov_b64 s[4:5], s[12:13]
	s_barrier
	v_readlane_b32 s1, v254, 58
	s_branch .LBB0_661

; #define LAS __attribute__((address_space(3)))
; #define PG8_STAGE(bufoff, gbase, voff) do { _Pragma("unroll") for (int _i = 0; _i < 2; ++_i) \
;         __builtin_amdgcn_global_load_lds((const unsigned*)((const char*)(gbase) + (voff)[_i]), (LAS unsigned*)(lds + (bufoff) + ldsw + _i * 8192), 16, 0, 0); } while (0)
; #define PG8_WAIT_V(n) asm volatile("s_waitcnt vmcnt(" #n ")" ::: "memory")
; #define PG8_BAR __builtin_amdgcn_s_barrier()
; template <class Epi>
; __device__ __forceinline__ void gemm_phase(LAS unsigned char* lds, const Gemm g, const TileOrder& S, const Epi& E) {
;     ...
;     PG8_STAGE(PG8_SB(0, 0), cB, voffB); PG8_STAGE(PG8_SB(0, 1), cB + hstepB, voffB); PG8_STAGE(PG8_SA(0, 0), cA, voffA); PG8_STAGE(PG8_SA(0, 1), cA + hstepA, voffA);
;     if (wr == 1) PG8_BAR;
;     PG8_WAIT_V(2); PG8_BAR;
;     PG8_STAGE(PG8_SB(1, 0), cB + kstep, voffB); PG8_STAGE(PG8_SA(1, 0), cA + kstepA, voffA); PG8_STAGE(PG8_SB(1, 1), cB + hstepB + kstep, voffB);
;     PG8_WAIT_V(6); PG8_BAR;
;     __device__ __forceinline__ void operator()(const f32x4 (&acc)[2][2][4][2], const Unit& u, int wr, int wc, int fr, int fq, LAS unsigned char* lds, int& estate) const {
;         asm volatile("" : "+v"(fr), "+v"(fq));
;         const int row0 = u.pm * BM + wr * 64 + fr, col0 = u.pn * BM + wc * 32 + 8 * fq;
;         panel_rstd(lds, ssp, nslot, u.pm, estate);
;         float rs[2][4];
; #pragma unroll
;         for (int ai = 0; ai < 2; ++ai)
; #pragma unroll
;             for (int m = 0; m < 4; ++m) rs[ai][m] = ((const LAS float*)(lds + RS_OFF))[wr * 64 + fr + ai * HALF + m * 16];
; #pragma unroll
;         for (int ai = 0; ai < 2; ++ai)
; #pragma unroll
;             for (int m = 0; m < 4; ++m) {
;                 bf16_t* rowp = O + (((size_t)u.pm * (DFF / 64) + (u.pn * 4 + (wc >> 1))) * 256 + (wr * 64 + fr + ai * HALF + m * 16)) * 64 + (wc & 1) * 32 + 8 * fq;
.LBB0_747:
	s_lshl_b64 s[12:13], s[24:25], 23
	v_readlane_b32 s14, v252, 52
	v_readlane_b32 s28, v254, 43
	s_add_u32 s38, s14, s12
	v_readlane_b32 s12, v252, 53
	v_mov_b32_e32 v137, v1
	v_readlane_b32 s29, v254, 44
	s_addc_u32 s39, s12, s13
	s_and_b32 s12, s0, 3
	s_add_i32 m0, s59, 0x18000
	v_lshl_add_u64 v[2:3], v[2:3], 0, s[34:35]
	v_lshl_add_u64 v[12:13], s[28:29], 0, v[136:137]
	v_mov_b32_e32 v133, v1
	s_lshl_b32 s25, s6, 6
	s_lshl_b32 s14, s6, 13
	s_lshl_b32 s15, s12, 12
	global_load_lds_dwordx4 v[2:3], off
	v_lshl_add_u64 v[2:3], v[4:5], 0, s[34:35]
	s_add_i32 m0, s59, 0x1a000
	s_add_i32 s63, s59, 0x8000
	s_add_i32 s64, s59, 0xa000
	v_lshl_add_u64 v[14:15], s[28:29], 0, v[132:133]
	global_load_lds_dwordx4 v[2:3], off
	v_lshl_add_u64 v[2:3], v[12:13], 0, s[34:35]
	s_mov_b32 m0, s63
	s_add_u32 s12, s2, 0x80080
	global_load_lds_dwordx4 v[2:3], off
	v_lshl_add_u64 v[2:3], v[14:15], 0, s[34:35]
	s_mov_b32 m0, s64
	s_addc_u32 s13, s3, 0
	global_load_lds_dwordx4 v[2:3], off
	s_add_i32 m0, s59, 0x1c000
	v_lshl_add_u64 v[2:3], s[12:13], 0, v[134:135]
	global_load_lds_dwordx4 v[2:3], off
	v_lshl_add_u64 v[2:3], s[12:13], 0, v[130:131]
	s_add_i32 m0, s59, 0x1e000
	v_bfe_u32 v153, v7, 4, 2
	global_load_lds_dwordx4 v[2:3], off
	s_waitcnt vmcnt(8)
	s_barrier
	v_and_b32_e32 v152, 15, v7
	v_lshlrev_b32_e32 v2, 4, v153
	v_lshlrev_b32_e32 v3, 2, v7
	v_lshl_or_b32 v2, v152, 6, v2
	v_and_b32_e32 v3, 32, v3
	v_bitop3_b32 v4, v2, s14, v3 bitop3:0xde
	v_bitop3_b32 v154, v2, s15, v3 bitop3:0xde
	v_lshlrev_b32_e32 v2, 15, v10
	v_and_b32_e32 v2, 0xffff0000, v2
	v_lshl_add_u32 v2, v9, 12, v2
	v_and_b32_e32 v3, 1, v10
	s_cmpk_lt_u32 s1, 0x100
	v_lshl_or_b32 v2, v3, 6, v2
	s_cselect_b64 s[42:43], -1, 0
	s_lshl_b32 s1, s6, 8
	v_lshl_add_u32 v138, v11, 1, v2
	v_lshlrev_b32_e32 v2, 15, v0
	s_add_i32 s65, s1, 0
	s_bfe_u32 s66, s0, 0x10001
	s_lshl_b32 s0, s0, 6
	v_and_b32_e32 v2, 0xffff0000, v2
	s_waitcnt vmcnt(6)
	s_add_i32 s65, s65, 0x20000
	s_and_b32 s0, s0, 64
	v_readlane_b32 s12, v255, 5
	v_lshl_add_u32 v2, v6, 12, v2
	v_and_b32_e32 v0, 1, v0
	v_readlane_b32 s13, v255, 6
	s_add_u32 s44, s12, s0
	v_lshl_or_b32 v0, v0, 6, v2
	s_addc_u32 s45, s13, 0
	v_mov_b32_e32 v139, v1
	v_lshl_add_u32 v140, v8, 1, v0
	v_mov_b32_e32 v141, v1
	s_mov_b32 s67, 0
	s_mov_b32 s41, -1
	v_add_u32_e32 v155, 0, v4
	v_readlane_b32 s68, v254, 35
	v_readlane_b32 s50, v254, 39
	s_barrier
	v_readlane_b32 s51, v254, 40
	s_branch .LBB0_750

; #define PG8_STAGE(bufoff, gbase, voff) do { _Pragma("unroll") for (int _i = 0; _i < 2; ++_i) \
;         __builtin_amdgcn_global_load_lds((const unsigned*)((const char*)(gbase) + (voff)[_i]), (LAS unsigned*)(lds + (bufoff) + ldsw + _i * 8192), 16, 0, 0); } while (0)
; #define PG8_WAIT_V(n) asm volatile("s_waitcnt vmcnt(" #n ")" ::: "memory")
; #define PG8_BAR __builtin_amdgcn_s_barrier()
; template <class Epi>
; __device__ __forceinline__ void gemm_phase(LAS unsigned char* lds, const Gemm g, const TileOrder& S, const Epi& E) {
;     ...
;     PG8_STAGE(PG8_SB(0, 0), cB, voffB); PG8_STAGE(PG8_SB(0, 1), cB + hstepB, voffB); PG8_STAGE(PG8_SA(0, 0), cA, voffA); PG8_STAGE(PG8_SA(0, 1), cA + hstepA, voffA);
;     if (wr == 1) PG8_BAR;
;     PG8_WAIT_V(2); PG8_BAR;
;     PG8_STAGE(PG8_SB(1, 0), cB + kstep, voffB); PG8_STAGE(PG8_SA(1, 0), cA + kstepA, voffA); PG8_STAGE(PG8_SB(1, 1), cB + hstepB + kstep, voffB);
;     PG8_WAIT_V(6); PG8_BAR;
; __global__ void __launch_bounds__(NTHR, 2) fwd_kernel(Args a) {
;     ...
;         {   pg8::Gemm g{HID, WDN + (size_t)layer * DM * DFF, DFF, DFF, DFF, 1}; pg8::TileOrder S; S.init(128, 8, G, bx, 0);
;             pg8::EpiResidual E{XN, is_s5 ? SS + (size_t)(4 + j) * SS_USE : nullptr, layer == 3 ? a.out : nullptr}; pg8::gemm_phase<pg8::EpiResidual>(lds, g, S, E); }
.LBB0_825:
	s_lshl_b32 s26, s84, 21
	s_lshl_b64 s[12:13], s[26:27], 2
	v_readlane_b32 s14, v252, 52
	s_add_u32 s12, s14, s12
	v_readlane_b32 s14, v252, 53
	s_addc_u32 s13, s14, s13
	s_add_u32 s26, s12, 0x2000000
	s_addc_u32 s64, s13, 0
	s_cmp_eq_u32 s24, 3
	v_bfe_u32 v238, v12, 4, 2
	s_cselect_b32 s37, s21, 0
	s_cselect_b32 s36, s20, 0
	v_and_b32_e32 v239, 15, v12
	v_lshlrev_b32_e32 v13, 4, v238
	v_lshlrev_b32_e32 v12, 2, v12
	s_add_i32 m0, s60, 0x18000
	v_lshl_add_u64 v[2:3], v[2:3], 0, s[34:35]
	v_readlane_b32 s12, v255, 12
	v_mov_b32_e32 v195, v1
	s_and_b32 s66, s6, 3
	s_lshl_b32 s67, s1, 6
	v_lshl_or_b32 v13, v239, 6, v13
	s_lshl_b32 s1, s1, 13
	v_and_b32_e32 v12, 32, v12
	global_load_lds_dwordx4 v[2:3], off
	v_lshl_add_u64 v[2:3], v[4:5], 0, s[34:35]
	s_add_i32 m0, s60, 0x1a000
	v_readlane_b32 s13, v255, 13
	s_add_i32 s69, s60, 0x8000
	v_mov_b32_e32 v193, v1
	v_bitop3_b32 v14, v13, s1, v12 bitop3:0xde
	s_lshl_b32 s68, s66, 5
	s_lshl_b32 s1, s66, 12
	global_load_lds_dwordx4 v[2:3], off
	v_lshl_add_u64 v[2:3], s[12:13], 0, v[194:195]
	s_mov_b32 m0, s69
	s_add_i32 s70, s60, 0xa000
	global_load_lds_dwordx4 v[2:3], off
	v_lshl_add_u64 v[2:3], s[12:13], 0, v[192:193]
	s_add_u32 s12, s2, 0x200080
	s_mov_b32 m0, s70
	s_addc_u32 s13, s3, 0
	global_load_lds_dwordx4 v[2:3], off
	s_add_i32 m0, s60, 0x1c000
	v_lshl_add_u64 v[2:3], s[12:13], 0, v[0:1]
	global_load_lds_dwordx4 v[2:3], off
	v_lshl_add_u64 v[2:3], s[12:13], 0, v[190:191]
	s_add_i32 m0, s60, 0x1e000
	s_cmpk_lt_u32 s0, 0x100
	global_load_lds_dwordx4 v[2:3], off
	s_waitcnt vmcnt(8)
	s_barrier
	v_lshlrev_b32_e32 v2, 10, v10
	v_and_b32_e32 v2, 0xfffff800, v2
	v_lshl_add_u32 v2, v9, 7, v2
	v_and_b32_e32 v3, 1, v10
	v_lshl_or_b32 v2, v3, 6, v2
	v_lshl_add_u32 v196, v11, 1, v2
	v_lshlrev_b32_e32 v2, 10, v6
	v_and_b32_e32 v2, 0xfffff800, v2
	s_waitcnt vmcnt(6)
	v_lshl_add_u32 v2, v7, 7, v2
	v_and_b32_e32 v3, 1, v6
	v_bitop3_b32 v240, v13, s1, v12 bitop3:0xde
	s_cselect_b64 s[46:47], -1, 0
	s_cmp_lg_u64 s[36:37], 0
	v_lshl_or_b32 v2, v3, 6, v2
	v_readlane_b32 s0, v255, 3
	v_readlane_b32 s28, v255, 10
	s_mov_b32 s65, 0
	s_cselect_b64 s[48:49], -1, 0
	v_mov_b32_e32 v197, v1
	v_lshl_add_u32 v198, v8, 1, v2
	v_mov_b32_e32 v199, v1
	v_add_u32_e32 v241, 0, v14
	v_readlane_b32 s44, v254, 7
	s_mov_b32 s41, s0
	v_readlane_b32 s29, v255, 11
	s_barrier
	v_readlane_b32 s1, v255, 4
	s_branch .LBB0_828
